# speedup vs baseline: 1.0047x; 1.0047x over previous
; template <class DescFn, class EpiFn>
; __device__ __forceinline__ void gemm_phase(int nM, int nN, DescFn dfn, EpiFn efn) {
;     ...
;     efn(cpm, cpn)(acc, wr, wc, fr, fq);
.LBB0_1405:
	s_setprio 2
	s_ashr_i32 s21, s20, 31
	s_lshl_b64 s[20:21], s[20:21], 19
	s_add_u32 s2, s28, s20
	s_addc_u32 s25, s29, s21
	s_lshl_b32 s40, s39, 8
	s_ashr_i32 s41, s40, 31
	s_lshl_b64 s[22:23], s[40:41], 1
	s_add_u32 s24, s2, s22
	s_addc_u32 s25, s25, s23
	s_add_u32 s2, s92, s20
	s_addc_u32 s20, s93, s21
	s_add_u32 s22, s2, s22
	s_addc_u32 s23, s20, s23
	v_readlane_b32 s20, v255, 15
	v_readlane_b32 s21, v255, 16
	s_load_dwordx2 s[20:21], s[20:21], 0x90
	v_lshlrev_b32_e32 v132, 2, v188
	v_lshl_add_u64 v[130:131], s[24:25], 0, v[196:197]
	v_lshlrev_b32_e32 v0, 1, v188
	v_lshl_add_u64 v[130:131], v[130:131], 0, v[0:1]
	s_waitcnt lgkmcnt(0)
	s_add_u32 s2, s20, s34
	s_addc_u32 s39, s21, 0
	s_lshl_b64 s[20:21], s[40:41], 2
	s_add_u32 s20, s2, s20
	s_addc_u32 s21, s39, s21
	v_and_b32_e32 v176, 63, v182
	v_and_b32_e32 v174, 0x300, v132
	v_lshl_add_u32 v174, v176, 2, v174
	global_load_dword v175, v174, s[20:21]
	v_lshrrev_b32_e32 v173, 6, v182
	v_lshlrev_b32_e32 v173, 9, v173
	v_add_u32_e32 v173, 0x10000, v173
	v_and_b32_e32 v172, 48, v132
	v_add_u32_e32 v172, v173, v172
	v_lshl_add_u32 v173, v176, 2, v173
	v_bfe_u32 v176, v182, 4, 1
	v_mul_u32_u24_e32 v176, 24, v176
	v_mov_b32_e32 v177, 0
	v_lshl_add_u64 v[170:171], v[130:131], 0, v[176:177]
	global_load_dwordx4 v[142:145], v[170:171], off
	global_load_dwordx4 v[146:149], v[170:171], off offset:64
	v_add_co_u32_e32 v170, vcc, 0x8000, v170
	s_nop 1
	v_addc_co_u32_e32 v171, vcc, 0, v171, vcc
	global_load_dwordx4 v[150:153], v[170:171], off
	global_load_dwordx4 v[154:157], v[170:171], off offset:64
	v_add_co_u32_e32 v170, vcc, 0x8000, v170
	s_nop 1
	v_addc_co_u32_e32 v171, vcc, 0, v171, vcc
	global_load_dwordx4 v[158:161], v[170:171], off
	global_load_dwordx4 v[162:165], v[170:171], off offset:64
	v_add_co_u32_e32 v170, vcc, 0x8000, v170
	s_nop 1
	v_addc_co_u32_e32 v171, vcc, 0, v171, vcc
	global_load_dwordx4 v[166:169], v[170:171], off
	s_waitcnt vmcnt(7)
	ds_write_b32 v173, v175
	s_waitcnt lgkmcnt(0)
	ds_read_b128 v[134:137], v172
	s_waitcnt vmcnt(6)
	v_permlane16_swap_b32_e32 v142, v144
	v_permlane16_swap_b32_e32 v143, v145
	v_mov_b64_e32 v[138:139], v[142:143]
	s_waitcnt lgkmcnt(0)
	v_add_f32_e32 v126, v126, v134
	v_add_f32_e32 v127, v127, v135
	v_mul_f32_e32 v126, 0xbfb8aa3b, v126
	v_mul_f32_e32 v127, 0xbfb8aa3b, v127
	v_exp_f32_e32 v126, v126
	v_exp_f32_e32 v127, v127
	v_lshlrev_b32_e32 v133, 16, v138
	v_and_b32_e32 v138, 0xffff0000, v138
	v_add_f32_e32 v126, 1.0, v126
	v_add_f32_e32 v127, 1.0, v127
	v_rcp_f32_e32 v126, v126
	v_rcp_f32_e32 v127, v127
	v_lshlrev_b32_e32 v140, 16, v139
	v_and_b32_e32 v139, 0xffff0000, v139
	v_mul_f32_e32 v126, v126, v133
	v_mul_f32_e32 v127, v127, v138
	v_cvt_pk_bf16_f32 v248, v126, v127
	v_add_f32_e32 v126, v128, v136
	v_add_f32_e32 v127, v129, v137
	v_mul_f32_e32 v126, 0xbfb8aa3b, v126
	v_mul_f32_e32 v127, 0xbfb8aa3b, v127
	v_exp_f32_e32 v126, v126
	v_exp_f32_e32 v127, v127
	v_add_f32_e32 v126, 1.0, v126
	v_add_f32_e32 v127, 1.0, v127
	v_rcp_f32_e32 v126, v126
	v_rcp_f32_e32 v127, v127
	v_mul_f32_e32 v126, v126, v140
	v_mul_f32_e32 v127, v127, v139
	v_cvt_pk_bf16_f32 v249, v126, v127
	v_lshl_add_u64 v[126:127], s[22:23], 0, v[196:197]
	v_lshl_add_u64 v[126:127], v[126:127], 0, v[0:1]
	s_waitcnt vmcnt(6)
	v_mov_b64_e32 v[128:129], v[144:145]
	global_load_dwordx4 v[142:145], v[170:171], off offset:64
	v_add_co_u32_e32 v170, vcc, 0x8000, v170
	s_nop 1
	v_addc_co_u32_e32 v171, vcc, 0, v171, vcc
	ds_read_b128 v[134:137], v172 offset:64
	v_lshlrev_b32_e32 v133, 16, v128
	s_waitcnt lgkmcnt(0)
	v_add_f32_e32 v122, v122, v134
	v_add_f32_e32 v123, v123, v135
	v_mul_f32_e32 v122, 0xbfb8aa3b, v122
	v_mul_f32_e32 v123, 0xbfb8aa3b, v123
	v_exp_f32_e32 v122, v122
	v_exp_f32_e32 v123, v123
	v_and_b32_e32 v128, 0xffff0000, v128
	v_lshlrev_b32_e32 v138, 16, v129
	v_add_f32_e32 v122, 1.0, v122
	v_add_f32_e32 v123, 1.0, v123
	v_rcp_f32_e32 v122, v122
	v_rcp_f32_e32 v123, v123
	v_and_b32_e32 v129, 0xffff0000, v129
	v_mul_f32_e32 v122, v122, v133
	v_mul_f32_e32 v123, v123, v128
	v_cvt_pk_bf16_f32 v250, v122, v123
	v_add_f32_e32 v123, v124, v136
	v_mul_f32_e32 v123, 0xbfb8aa3b, v123
	v_add_f32_e32 v124, v125, v137
	v_exp_f32_e32 v123, v123
	v_mul_f32_e32 v124, 0xbfb8aa3b, v124
	v_exp_f32_e32 v124, v124
	v_add_f32_e32 v123, 1.0, v123
	v_rcp_f32_e32 v123, v123
	v_add_f32_e32 v124, 1.0, v124
	v_rcp_f32_e32 v124, v124
	v_mul_f32_e32 v123, v123, v138
	v_mul_f32_e32 v124, v124, v129
	v_cvt_pk_bf16_f32 v251, v123, v124
	v_lshl_add_u64 v[252:253], v[126:127], 0, v[176:177]
	s_nop 1
	v_permlane16_swap_b32_e32 v248, v250
	v_permlane16_swap_b32_e32 v249, v251
	global_store_dwordx4 v[252:253], v[248:251], off
	s_waitcnt vmcnt(7)
	v_permlane16_swap_b32_e32 v146, v148
	v_permlane16_swap_b32_e32 v147, v149
	v_mov_b64_e32 v[128:129], v[146:147]
	ds_read_b128 v[122:125], v172 offset:128
	v_lshlrev_b32_e32 v133, 16, v128
	s_waitcnt lgkmcnt(0)
	v_add_f32_e32 v118, v118, v122
	v_add_f32_e32 v119, v119, v123
	v_mul_f32_e32 v118, 0xbfb8aa3b, v118
	v_mul_f32_e32 v119, 0xbfb8aa3b, v119
	v_exp_f32_e32 v118, v118
	v_exp_f32_e32 v119, v119
	v_and_b32_e32 v128, 0xffff0000, v128
	v_lshlrev_b32_e32 v134, 16, v129
	v_add_f32_e32 v118, 1.0, v118
	v_add_f32_e32 v119, 1.0, v119
	v_rcp_f32_e32 v118, v118
	v_rcp_f32_e32 v119, v119
	v_and_b32_e32 v129, 0xffff0000, v129
	v_mul_f32_e32 v118, v118, v133
	v_mul_f32_e32 v119, v119, v128
	v_cvt_pk_bf16_f32 v248, v118, v119
	v_add_f32_e32 v119, v120, v124
	v_mul_f32_e32 v119, 0xbfb8aa3b, v119
	v_add_f32_e32 v120, v121, v125
	v_exp_f32_e32 v119, v119
	v_mul_f32_e32 v120, 0xbfb8aa3b, v120
	v_exp_f32_e32 v120, v120
	v_add_f32_e32 v119, 1.0, v119
	v_rcp_f32_e32 v119, v119
	v_add_f32_e32 v120, 1.0, v120
	v_rcp_f32_e32 v120, v120
	v_mul_f32_e32 v119, v119, v134
	v_mul_f32_e32 v120, v120, v129
	v_cvt_pk_bf16_f32 v249, v119, v120
	s_waitcnt vmcnt(7)
	v_mov_b64_e32 v[118:119], v[148:149]
	global_load_dwordx4 v[146:149], v[170:171], off
	ds_read_b128 v[120:123], v172 offset:192
	v_lshlrev_b32_e32 v124, 16, v118
	s_waitcnt lgkmcnt(0)
	v_add_f32_e32 v114, v114, v120
	v_add_f32_e32 v115, v115, v121
	v_mul_f32_e32 v114, 0xbfb8aa3b, v114
	v_mul_f32_e32 v115, 0xbfb8aa3b, v115
	v_exp_f32_e32 v114, v114
	v_exp_f32_e32 v115, v115
	v_and_b32_e32 v118, 0xffff0000, v118
	v_lshlrev_b32_e32 v125, 16, v119
	v_add_f32_e32 v114, 1.0, v114
	v_add_f32_e32 v115, 1.0, v115
	v_rcp_f32_e32 v114, v114
	v_rcp_f32_e32 v115, v115
	v_and_b32_e32 v119, 0xffff0000, v119
	v_mul_f32_e32 v114, v114, v124
	v_mul_f32_e32 v115, v115, v118
	v_cvt_pk_bf16_f32 v250, v114, v115
	v_add_f32_e32 v115, v116, v122
	v_mul_f32_e32 v115, 0xbfb8aa3b, v115
	v_add_f32_e32 v116, v117, v123
	v_exp_f32_e32 v115, v115
	v_mul_f32_e32 v116, 0xbfb8aa3b, v116
	v_exp_f32_e32 v116, v116
	v_add_f32_e32 v115, 1.0, v115
	v_rcp_f32_e32 v115, v115
	v_add_f32_e32 v116, 1.0, v116
	v_rcp_f32_e32 v116, v116
	v_mul_f32_e32 v115, v115, v125
	v_mul_f32_e32 v116, v116, v119
	v_cvt_pk_bf16_f32 v251, v115, v116
	v_lshl_add_u64 v[252:253], v[126:127], 0, v[176:177]
	s_nop 1
	v_permlane16_swap_b32_e32 v248, v250
	v_permlane16_swap_b32_e32 v249, v251
	global_store_dwordx4 v[252:253], v[248:251], off offset:64
	v_lshl_add_u64 v[114:115], s[24:25], 0, v[198:199]
	v_lshl_add_u64 v[114:115], v[114:115], 0, v[0:1]
	s_waitcnt vmcnt(8)
	v_permlane16_swap_b32_e32 v150, v152
	v_permlane16_swap_b32_e32 v151, v153
	v_mov_b64_e32 v[120:121], v[150:151]
	ds_read_b128 v[116:119], v172
	v_lshlrev_b32_e32 v122, 16, v120
	s_waitcnt lgkmcnt(0)
	v_add_f32_e32 v110, v110, v116
	v_add_f32_e32 v111, v111, v117
	v_mul_f32_e32 v110, 0xbfb8aa3b, v110
	v_mul_f32_e32 v111, 0xbfb8aa3b, v111
	v_exp_f32_e32 v110, v110
	v_exp_f32_e32 v111, v111
	v_and_b32_e32 v120, 0xffff0000, v120
	v_lshlrev_b32_e32 v123, 16, v121
	v_add_f32_e32 v110, 1.0, v110
	v_add_f32_e32 v111, 1.0, v111
	v_rcp_f32_e32 v110, v110
	v_rcp_f32_e32 v111, v111
	v_and_b32_e32 v121, 0xffff0000, v121
	v_mul_f32_e32 v110, v110, v122
	v_mul_f32_e32 v111, v111, v120
	v_cvt_pk_bf16_f32 v248, v110, v111
	v_add_f32_e32 v110, v112, v118
	v_add_f32_e32 v111, v113, v119
	v_mul_f32_e32 v110, 0xbfb8aa3b, v110
	v_mul_f32_e32 v111, 0xbfb8aa3b, v111
	v_exp_f32_e32 v110, v110
	v_exp_f32_e32 v111, v111
	v_add_f32_e32 v110, 1.0, v110
	v_add_f32_e32 v111, 1.0, v111
	v_rcp_f32_e32 v110, v110
	v_rcp_f32_e32 v111, v111
	v_mul_f32_e32 v110, v110, v123
	v_mul_f32_e32 v111, v111, v121
	v_cvt_pk_bf16_f32 v249, v110, v111
	v_lshl_add_u64 v[110:111], s[22:23], 0, v[198:199]
	v_lshl_add_u64 v[110:111], v[110:111], 0, v[0:1]
	s_waitcnt vmcnt(8)
	v_mov_b64_e32 v[112:113], v[152:153]
	global_load_dwordx4 v[150:153], v[170:171], off offset:64
	v_add_co_u32_e32 v170, vcc, 0x8000, v170
	s_nop 1
	v_addc_co_u32_e32 v171, vcc, 0, v171, vcc
	ds_read_b128 v[116:119], v172 offset:64
	v_lshlrev_b32_e32 v120, 16, v112
	s_waitcnt lgkmcnt(0)
	v_add_f32_e32 v106, v106, v116
	v_add_f32_e32 v107, v107, v117
	v_mul_f32_e32 v106, 0xbfb8aa3b, v106
	v_mul_f32_e32 v107, 0xbfb8aa3b, v107
	v_exp_f32_e32 v106, v106
	v_exp_f32_e32 v107, v107
	v_and_b32_e32 v112, 0xffff0000, v112
	v_lshlrev_b32_e32 v121, 16, v113
	v_add_f32_e32 v106, 1.0, v106
	v_add_f32_e32 v107, 1.0, v107
	v_rcp_f32_e32 v106, v106
	v_rcp_f32_e32 v107, v107
	v_and_b32_e32 v113, 0xffff0000, v113
	v_mul_f32_e32 v106, v106, v120
	v_mul_f32_e32 v107, v107, v112
	v_cvt_pk_bf16_f32 v250, v106, v107
	v_add_f32_e32 v107, v108, v118
	v_mul_f32_e32 v107, 0xbfb8aa3b, v107
	v_add_f32_e32 v108, v109, v119
	v_exp_f32_e32 v107, v107
	v_mul_f32_e32 v108, 0xbfb8aa3b, v108
	v_exp_f32_e32 v108, v108
	v_add_f32_e32 v107, 1.0, v107
	v_rcp_f32_e32 v107, v107
	v_add_f32_e32 v108, 1.0, v108
	v_rcp_f32_e32 v108, v108
	v_mul_f32_e32 v107, v107, v121
	v_mul_f32_e32 v108, v108, v113
	v_cvt_pk_bf16_f32 v251, v107, v108
	v_lshl_add_u64 v[252:253], v[110:111], 0, v[176:177]
	s_nop 1
	v_permlane16_swap_b32_e32 v248, v250
	v_permlane16_swap_b32_e32 v249, v251
	global_store_dwordx4 v[252:253], v[248:251], off
	s_waitcnt vmcnt(9)
	v_permlane16_swap_b32_e32 v154, v156
	v_permlane16_swap_b32_e32 v155, v157
	v_mov_b64_e32 v[112:113], v[154:155]
	ds_read_b128 v[106:109], v172 offset:128
	v_lshlrev_b32_e32 v116, 16, v112
	s_waitcnt lgkmcnt(0)
	v_add_f32_e32 v102, v102, v106
	v_add_f32_e32 v103, v103, v107
	v_mul_f32_e32 v102, 0xbfb8aa3b, v102
	v_mul_f32_e32 v103, 0xbfb8aa3b, v103
	v_exp_f32_e32 v102, v102
	v_exp_f32_e32 v103, v103
	v_and_b32_e32 v112, 0xffff0000, v112
	v_lshlrev_b32_e32 v117, 16, v113
	v_add_f32_e32 v102, 1.0, v102
	v_add_f32_e32 v103, 1.0, v103
	v_rcp_f32_e32 v102, v102
	v_rcp_f32_e32 v103, v103
	v_and_b32_e32 v113, 0xffff0000, v113
	v_mul_f32_e32 v102, v102, v116
	v_mul_f32_e32 v103, v103, v112
	v_cvt_pk_bf16_f32 v248, v102, v103
	v_add_f32_e32 v103, v104, v108
	v_mul_f32_e32 v103, 0xbfb8aa3b, v103
	v_add_f32_e32 v104, v105, v109
	v_exp_f32_e32 v103, v103
	v_mul_f32_e32 v104, 0xbfb8aa3b, v104
	v_exp_f32_e32 v104, v104
	v_add_f32_e32 v103, 1.0, v103
	v_rcp_f32_e32 v103, v103
	v_add_f32_e32 v104, 1.0, v104
	v_rcp_f32_e32 v104, v104
	v_mul_f32_e32 v103, v103, v117
	v_mul_f32_e32 v104, v104, v113
	v_cvt_pk_bf16_f32 v249, v103, v104
	s_waitcnt vmcnt(9)
	v_mov_b64_e32 v[102:103], v[156:157]
	global_load_dwordx4 v[154:157], v[170:171], off
	ds_read_b128 v[104:107], v172 offset:192
	v_lshlrev_b32_e32 v108, 16, v102
	s_waitcnt lgkmcnt(0)
	v_add_f32_e32 v98, v98, v104
	v_add_f32_e32 v99, v99, v105
	v_mul_f32_e32 v98, 0xbfb8aa3b, v98
	v_mul_f32_e32 v99, 0xbfb8aa3b, v99
	v_exp_f32_e32 v98, v98
	v_exp_f32_e32 v99, v99
	v_and_b32_e32 v102, 0xffff0000, v102
	v_lshlrev_b32_e32 v109, 16, v103
	v_add_f32_e32 v98, 1.0, v98
	v_add_f32_e32 v99, 1.0, v99
	v_rcp_f32_e32 v98, v98
	v_rcp_f32_e32 v99, v99
	v_and_b32_e32 v103, 0xffff0000, v103
	v_mul_f32_e32 v98, v98, v108
	v_mul_f32_e32 v99, v99, v102
	v_cvt_pk_bf16_f32 v250, v98, v99
	v_add_f32_e32 v99, v100, v106
	v_mul_f32_e32 v99, 0xbfb8aa3b, v99
	v_add_f32_e32 v100, v101, v107
	v_exp_f32_e32 v99, v99
	v_mul_f32_e32 v100, 0xbfb8aa3b, v100
	v_exp_f32_e32 v100, v100
	v_add_f32_e32 v99, 1.0, v99
	v_rcp_f32_e32 v99, v99
	v_add_f32_e32 v100, 1.0, v100
	v_rcp_f32_e32 v100, v100
	v_mul_f32_e32 v99, v99, v109
	v_mul_f32_e32 v100, v100, v103
	v_cvt_pk_bf16_f32 v251, v99, v100
	v_lshl_add_u64 v[252:253], v[110:111], 0, v[176:177]
	s_nop 1
	v_permlane16_swap_b32_e32 v248, v250
	v_permlane16_swap_b32_e32 v249, v251
	global_store_dwordx4 v[252:253], v[248:251], off offset:64
	v_lshl_add_u64 v[98:99], s[24:25], 0, v[200:201]
	v_lshl_add_u64 v[98:99], v[98:99], 0, v[0:1]
	s_waitcnt vmcnt(10)
	v_permlane16_swap_b32_e32 v158, v160
	v_permlane16_swap_b32_e32 v159, v161
	v_mov_b64_e32 v[104:105], v[158:159]
	ds_read_b128 v[100:103], v172
	v_lshlrev_b32_e32 v106, 16, v104
	s_waitcnt lgkmcnt(0)
	v_add_f32_e32 v94, v94, v100
	v_add_f32_e32 v95, v95, v101
	v_mul_f32_e32 v94, 0xbfb8aa3b, v94
	v_mul_f32_e32 v95, 0xbfb8aa3b, v95
	v_exp_f32_e32 v94, v94
	v_exp_f32_e32 v95, v95
	v_and_b32_e32 v104, 0xffff0000, v104
	v_lshlrev_b32_e32 v107, 16, v105
	v_add_f32_e32 v94, 1.0, v94
	v_add_f32_e32 v95, 1.0, v95
	v_rcp_f32_e32 v94, v94
	v_rcp_f32_e32 v95, v95
	v_and_b32_e32 v105, 0xffff0000, v105
	v_mul_f32_e32 v94, v94, v106
	v_mul_f32_e32 v95, v95, v104
	v_cvt_pk_bf16_f32 v248, v94, v95
	v_add_f32_e32 v94, v96, v102
	v_add_f32_e32 v95, v97, v103
	v_mul_f32_e32 v94, 0xbfb8aa3b, v94
	v_mul_f32_e32 v95, 0xbfb8aa3b, v95
	v_exp_f32_e32 v94, v94
	v_exp_f32_e32 v95, v95
	v_add_f32_e32 v94, 1.0, v94
	v_add_f32_e32 v95, 1.0, v95
	v_rcp_f32_e32 v94, v94
	v_rcp_f32_e32 v95, v95
	v_mul_f32_e32 v94, v94, v107
	v_mul_f32_e32 v95, v95, v105
	v_cvt_pk_bf16_f32 v249, v94, v95
	v_lshl_add_u64 v[94:95], s[22:23], 0, v[200:201]
	v_lshl_add_u64 v[94:95], v[94:95], 0, v[0:1]
	s_waitcnt vmcnt(10)
	v_mov_b64_e32 v[96:97], v[160:161]
	global_load_dwordx4 v[158:161], v[170:171], off offset:64
	v_add_co_u32_e32 v170, vcc, 0x8000, v170
	s_nop 1
	v_addc_co_u32_e32 v171, vcc, 0, v171, vcc
	ds_read_b128 v[100:103], v172 offset:64
	v_lshlrev_b32_e32 v104, 16, v96
	s_waitcnt lgkmcnt(0)
	v_add_f32_e32 v90, v90, v100
	v_add_f32_e32 v91, v91, v101
	v_mul_f32_e32 v90, 0xbfb8aa3b, v90
	v_mul_f32_e32 v91, 0xbfb8aa3b, v91
	v_exp_f32_e32 v90, v90
	v_exp_f32_e32 v91, v91
	v_and_b32_e32 v96, 0xffff0000, v96
	v_lshlrev_b32_e32 v105, 16, v97
	v_add_f32_e32 v90, 1.0, v90
	v_add_f32_e32 v91, 1.0, v91
	v_rcp_f32_e32 v90, v90
	v_rcp_f32_e32 v91, v91
	v_and_b32_e32 v97, 0xffff0000, v97
	v_mul_f32_e32 v90, v90, v104
	v_mul_f32_e32 v91, v91, v96
	v_cvt_pk_bf16_f32 v250, v90, v91
	v_add_f32_e32 v91, v92, v102
	v_mul_f32_e32 v91, 0xbfb8aa3b, v91
	v_add_f32_e32 v92, v93, v103
	v_exp_f32_e32 v91, v91
	v_mul_f32_e32 v92, 0xbfb8aa3b, v92
	v_exp_f32_e32 v92, v92
	v_add_f32_e32 v91, 1.0, v91
	v_rcp_f32_e32 v91, v91
	v_add_f32_e32 v92, 1.0, v92
	v_rcp_f32_e32 v92, v92
	v_mul_f32_e32 v91, v91, v105
	v_mul_f32_e32 v92, v92, v97
	v_cvt_pk_bf16_f32 v251, v91, v92
	v_lshl_add_u64 v[252:253], v[94:95], 0, v[176:177]
	s_nop 1
	v_permlane16_swap_b32_e32 v248, v250
	v_permlane16_swap_b32_e32 v249, v251
	global_store_dwordx4 v[252:253], v[248:251], off
	s_waitcnt vmcnt(11)
	v_permlane16_swap_b32_e32 v162, v164
	v_permlane16_swap_b32_e32 v163, v165
	v_mov_b64_e32 v[96:97], v[162:163]
	ds_read_b128 v[90:93], v172 offset:128
	v_lshlrev_b32_e32 v100, 16, v96
	s_waitcnt lgkmcnt(0)
	v_add_f32_e32 v86, v86, v90
	v_add_f32_e32 v87, v87, v91
	v_mul_f32_e32 v86, 0xbfb8aa3b, v86
	v_mul_f32_e32 v87, 0xbfb8aa3b, v87
	v_exp_f32_e32 v86, v86
	v_exp_f32_e32 v87, v87
	v_and_b32_e32 v96, 0xffff0000, v96
	v_lshlrev_b32_e32 v101, 16, v97
	v_add_f32_e32 v86, 1.0, v86
	v_add_f32_e32 v87, 1.0, v87
	v_rcp_f32_e32 v86, v86
	v_rcp_f32_e32 v87, v87
	v_and_b32_e32 v97, 0xffff0000, v97
	v_mul_f32_e32 v86, v86, v100
	v_mul_f32_e32 v87, v87, v96
	v_cvt_pk_bf16_f32 v248, v86, v87
	v_add_f32_e32 v87, v88, v92
	v_mul_f32_e32 v87, 0xbfb8aa3b, v87
	v_add_f32_e32 v88, v89, v93
	v_exp_f32_e32 v87, v87
	v_mul_f32_e32 v88, 0xbfb8aa3b, v88
	v_exp_f32_e32 v88, v88
	v_add_f32_e32 v87, 1.0, v87
	v_rcp_f32_e32 v87, v87
	v_add_f32_e32 v88, 1.0, v88
	v_rcp_f32_e32 v88, v88
	v_mul_f32_e32 v87, v87, v101
	v_mul_f32_e32 v88, v88, v97
	v_cvt_pk_bf16_f32 v249, v87, v88
	s_waitcnt vmcnt(11)
	v_mov_b64_e32 v[86:87], v[164:165]
	global_load_dwordx4 v[162:165], v[170:171], off
	ds_read_b128 v[88:91], v172 offset:192
	v_lshlrev_b32_e32 v92, 16, v86
	s_waitcnt lgkmcnt(0)
	v_add_f32_e32 v82, v82, v88
	v_add_f32_e32 v83, v83, v89
	v_mul_f32_e32 v82, 0xbfb8aa3b, v82
	v_mul_f32_e32 v83, 0xbfb8aa3b, v83
	v_exp_f32_e32 v82, v82
	v_exp_f32_e32 v83, v83
	v_and_b32_e32 v86, 0xffff0000, v86
	v_lshlrev_b32_e32 v93, 16, v87
	v_add_f32_e32 v82, 1.0, v82
	v_add_f32_e32 v83, 1.0, v83
	v_rcp_f32_e32 v82, v82
	v_rcp_f32_e32 v83, v83
	v_and_b32_e32 v87, 0xffff0000, v87
	v_mul_f32_e32 v82, v82, v92
	v_mul_f32_e32 v83, v83, v86
	v_cvt_pk_bf16_f32 v250, v82, v83
	v_add_f32_e32 v83, v84, v90
	v_mul_f32_e32 v83, 0xbfb8aa3b, v83
	v_add_f32_e32 v84, v85, v91
	v_exp_f32_e32 v83, v83
	v_mul_f32_e32 v84, 0xbfb8aa3b, v84
	v_exp_f32_e32 v84, v84
	v_add_f32_e32 v83, 1.0, v83
	v_rcp_f32_e32 v83, v83
	v_add_f32_e32 v84, 1.0, v84
	v_rcp_f32_e32 v84, v84
	v_mul_f32_e32 v83, v83, v93
	v_mul_f32_e32 v84, v84, v87
	v_cvt_pk_bf16_f32 v251, v83, v84
	v_lshl_add_u64 v[252:253], v[94:95], 0, v[176:177]
	s_nop 1
	v_permlane16_swap_b32_e32 v248, v250
	v_permlane16_swap_b32_e32 v249, v251
	global_store_dwordx4 v[252:253], v[248:251], off offset:64
	v_lshl_add_u64 v[82:83], s[24:25], 0, v[202:203]
	v_lshl_add_u64 v[82:83], v[82:83], 0, v[0:1]
	s_waitcnt vmcnt(12)
	v_permlane16_swap_b32_e32 v166, v168
	v_permlane16_swap_b32_e32 v167, v169
	v_mov_b64_e32 v[88:89], v[166:167]
	ds_read_b128 v[84:87], v172
	v_lshlrev_b32_e32 v90, 16, v88
	s_waitcnt lgkmcnt(0)
	v_add_f32_e32 v78, v78, v84
	v_add_f32_e32 v79, v79, v85
	v_mul_f32_e32 v78, 0xbfb8aa3b, v78
	v_mul_f32_e32 v79, 0xbfb8aa3b, v79
	v_exp_f32_e32 v78, v78
	v_exp_f32_e32 v79, v79
	v_and_b32_e32 v88, 0xffff0000, v88
	v_lshlrev_b32_e32 v91, 16, v89
	v_add_f32_e32 v78, 1.0, v78
	v_add_f32_e32 v79, 1.0, v79
	v_rcp_f32_e32 v78, v78
	v_rcp_f32_e32 v79, v79
	v_and_b32_e32 v89, 0xffff0000, v89
	v_mul_f32_e32 v78, v78, v90
	v_mul_f32_e32 v79, v79, v88
	v_cvt_pk_bf16_f32 v248, v78, v79
	v_add_f32_e32 v78, v80, v86
	v_add_f32_e32 v79, v81, v87
	v_mul_f32_e32 v78, 0xbfb8aa3b, v78
	v_mul_f32_e32 v79, 0xbfb8aa3b, v79
	v_exp_f32_e32 v78, v78
	v_exp_f32_e32 v79, v79
	v_add_f32_e32 v78, 1.0, v78
	v_add_f32_e32 v79, 1.0, v79
	v_rcp_f32_e32 v78, v78
	v_rcp_f32_e32 v79, v79
	v_mul_f32_e32 v78, v78, v91
	v_mul_f32_e32 v79, v79, v89
	v_cvt_pk_bf16_f32 v249, v78, v79
	v_lshl_add_u64 v[78:79], s[22:23], 0, v[202:203]
	v_lshl_add_u64 v[78:79], v[78:79], 0, v[0:1]
	s_waitcnt vmcnt(12)
	v_mov_b64_e32 v[80:81], v[168:169]
	global_load_dwordx4 v[166:169], v[170:171], off offset:64
	v_add_co_u32_e32 v170, vcc, 0x8000, v170
	s_nop 1
	v_addc_co_u32_e32 v171, vcc, 0, v171, vcc
	ds_read_b128 v[84:87], v172 offset:64
	v_lshlrev_b32_e32 v88, 16, v80
	s_waitcnt lgkmcnt(0)
	v_add_f32_e32 v74, v74, v84
	v_add_f32_e32 v75, v75, v85
	v_mul_f32_e32 v74, 0xbfb8aa3b, v74
	v_mul_f32_e32 v75, 0xbfb8aa3b, v75
	v_exp_f32_e32 v74, v74
	v_exp_f32_e32 v75, v75
	v_and_b32_e32 v80, 0xffff0000, v80
	v_lshlrev_b32_e32 v89, 16, v81
	v_add_f32_e32 v74, 1.0, v74
	v_add_f32_e32 v75, 1.0, v75
	v_rcp_f32_e32 v74, v74
	v_rcp_f32_e32 v75, v75
	v_and_b32_e32 v81, 0xffff0000, v81
	v_mul_f32_e32 v74, v74, v88
	v_mul_f32_e32 v75, v75, v80
	v_cvt_pk_bf16_f32 v250, v74, v75
	v_add_f32_e32 v75, v76, v86
	v_mul_f32_e32 v75, 0xbfb8aa3b, v75
	v_add_f32_e32 v76, v77, v87
	v_exp_f32_e32 v75, v75
	v_mul_f32_e32 v76, 0xbfb8aa3b, v76
	v_exp_f32_e32 v76, v76
	v_add_f32_e32 v75, 1.0, v75
	v_rcp_f32_e32 v75, v75
	v_add_f32_e32 v76, 1.0, v76
	v_rcp_f32_e32 v76, v76
	v_mul_f32_e32 v75, v75, v89
	v_mul_f32_e32 v76, v76, v81
	v_cvt_pk_bf16_f32 v251, v75, v76
	v_lshl_add_u64 v[252:253], v[78:79], 0, v[176:177]
	s_nop 1
	v_permlane16_swap_b32_e32 v248, v250
	v_permlane16_swap_b32_e32 v249, v251
	global_store_dwordx4 v[252:253], v[248:251], off
	s_waitcnt vmcnt(13)
	v_permlane16_swap_b32_e32 v142, v144
	v_permlane16_swap_b32_e32 v143, v145
	v_mov_b64_e32 v[80:81], v[142:143]
	ds_read_b128 v[74:77], v172 offset:128
	v_lshlrev_b32_e32 v84, 16, v80
	s_waitcnt lgkmcnt(0)
	v_add_f32_e32 v70, v70, v74
	v_add_f32_e32 v71, v71, v75
	v_mul_f32_e32 v70, 0xbfb8aa3b, v70
	v_mul_f32_e32 v71, 0xbfb8aa3b, v71
	v_exp_f32_e32 v70, v70
	v_exp_f32_e32 v71, v71
	v_and_b32_e32 v80, 0xffff0000, v80
	v_lshlrev_b32_e32 v85, 16, v81
	v_add_f32_e32 v70, 1.0, v70
	v_add_f32_e32 v71, 1.0, v71
	v_rcp_f32_e32 v70, v70
	v_rcp_f32_e32 v71, v71
	v_and_b32_e32 v81, 0xffff0000, v81
	v_mul_f32_e32 v70, v70, v84
	v_mul_f32_e32 v71, v71, v80
	v_cvt_pk_bf16_f32 v248, v70, v71
	v_add_f32_e32 v71, v72, v76
	v_mul_f32_e32 v71, 0xbfb8aa3b, v71
	v_add_f32_e32 v72, v73, v77
	v_exp_f32_e32 v71, v71
	v_mul_f32_e32 v72, 0xbfb8aa3b, v72
	v_exp_f32_e32 v72, v72
	v_add_f32_e32 v71, 1.0, v71
	v_rcp_f32_e32 v71, v71
	v_add_f32_e32 v72, 1.0, v72
	v_rcp_f32_e32 v72, v72
	v_mul_f32_e32 v71, v71, v85
	v_mul_f32_e32 v72, v72, v81
	v_cvt_pk_bf16_f32 v249, v71, v72
	s_waitcnt vmcnt(13)
	v_mov_b64_e32 v[70:71], v[144:145]
	global_load_dwordx4 v[142:145], v[170:171], off
	ds_read_b128 v[72:75], v172 offset:192
	v_lshlrev_b32_e32 v76, 16, v70
	s_waitcnt lgkmcnt(0)
	v_add_f32_e32 v66, v66, v72
	v_add_f32_e32 v67, v67, v73
	v_mul_f32_e32 v66, 0xbfb8aa3b, v66
	v_mul_f32_e32 v67, 0xbfb8aa3b, v67
	v_exp_f32_e32 v66, v66
	v_exp_f32_e32 v67, v67
	v_and_b32_e32 v70, 0xffff0000, v70
	v_lshlrev_b32_e32 v77, 16, v71
	v_add_f32_e32 v66, 1.0, v66
	v_add_f32_e32 v67, 1.0, v67
	v_rcp_f32_e32 v66, v66
	v_rcp_f32_e32 v67, v67
	v_and_b32_e32 v71, 0xffff0000, v71
	v_mul_f32_e32 v66, v66, v76
	v_mul_f32_e32 v67, v67, v70
	v_cvt_pk_bf16_f32 v250, v66, v67
	v_add_f32_e32 v67, v68, v74
	v_mul_f32_e32 v67, 0xbfb8aa3b, v67
	v_add_f32_e32 v68, v69, v75
	v_exp_f32_e32 v67, v67
	v_mul_f32_e32 v68, 0xbfb8aa3b, v68
	v_exp_f32_e32 v68, v68
	v_add_f32_e32 v67, 1.0, v67
	v_rcp_f32_e32 v67, v67
	v_add_f32_e32 v68, 1.0, v68
	v_rcp_f32_e32 v68, v68
	v_mul_f32_e32 v67, v67, v77
	v_mul_f32_e32 v68, v68, v71
	v_cvt_pk_bf16_f32 v251, v67, v68
	v_lshl_add_u64 v[252:253], v[78:79], 0, v[176:177]
	s_nop 1
	v_permlane16_swap_b32_e32 v248, v250
	v_permlane16_swap_b32_e32 v249, v251
	global_store_dwordx4 v[252:253], v[248:251], off offset:64
	v_lshl_add_u64 v[66:67], s[24:25], 0, v[204:205]
	v_lshl_add_u64 v[66:67], v[66:67], 0, v[0:1]
	s_waitcnt vmcnt(13)
	v_permlane16_swap_b32_e32 v146, v148
	v_permlane16_swap_b32_e32 v147, v149
	v_mov_b64_e32 v[72:73], v[146:147]
	ds_read_b128 v[68:71], v172
	v_lshlrev_b32_e32 v74, 16, v72
	s_waitcnt lgkmcnt(0)
	v_add_f32_e32 v62, v62, v68
	v_add_f32_e32 v63, v63, v69
	v_mul_f32_e32 v62, 0xbfb8aa3b, v62
	v_mul_f32_e32 v63, 0xbfb8aa3b, v63
	v_exp_f32_e32 v62, v62
	v_exp_f32_e32 v63, v63
	v_and_b32_e32 v72, 0xffff0000, v72
	v_lshlrev_b32_e32 v75, 16, v73
	v_add_f32_e32 v62, 1.0, v62
	v_add_f32_e32 v63, 1.0, v63
	v_rcp_f32_e32 v62, v62
	v_rcp_f32_e32 v63, v63
	v_and_b32_e32 v73, 0xffff0000, v73
	v_mul_f32_e32 v62, v62, v74
	v_mul_f32_e32 v63, v63, v72
	v_cvt_pk_bf16_f32 v248, v62, v63
	v_add_f32_e32 v62, v64, v70
	v_add_f32_e32 v63, v65, v71
	v_mul_f32_e32 v62, 0xbfb8aa3b, v62
	v_mul_f32_e32 v63, 0xbfb8aa3b, v63
	v_exp_f32_e32 v62, v62
	v_exp_f32_e32 v63, v63
	v_add_f32_e32 v62, 1.0, v62
	v_add_f32_e32 v63, 1.0, v63
	v_rcp_f32_e32 v62, v62
	v_rcp_f32_e32 v63, v63
	v_mul_f32_e32 v62, v62, v75
	v_mul_f32_e32 v63, v63, v73
	v_cvt_pk_bf16_f32 v249, v62, v63
	v_lshl_add_u64 v[62:63], s[22:23], 0, v[204:205]
	v_lshl_add_u64 v[62:63], v[62:63], 0, v[0:1]
	s_waitcnt vmcnt(13)
	v_mov_b64_e32 v[64:65], v[148:149]
	global_load_dwordx4 v[146:149], v[170:171], off offset:64
	ds_read_b128 v[68:71], v172 offset:64
	v_lshlrev_b32_e32 v72, 16, v64
	s_waitcnt lgkmcnt(0)
	v_add_f32_e32 v58, v58, v68
	v_add_f32_e32 v59, v59, v69
	v_mul_f32_e32 v58, 0xbfb8aa3b, v58
	v_mul_f32_e32 v59, 0xbfb8aa3b, v59
	v_exp_f32_e32 v58, v58
	v_exp_f32_e32 v59, v59
	v_and_b32_e32 v64, 0xffff0000, v64
	v_lshlrev_b32_e32 v73, 16, v65
	v_add_f32_e32 v58, 1.0, v58
	v_add_f32_e32 v59, 1.0, v59
	v_rcp_f32_e32 v58, v58
	v_rcp_f32_e32 v59, v59
	v_and_b32_e32 v65, 0xffff0000, v65
	v_mul_f32_e32 v58, v58, v72
	v_mul_f32_e32 v59, v59, v64
	v_cvt_pk_bf16_f32 v250, v58, v59
	v_add_f32_e32 v59, v60, v70
	v_mul_f32_e32 v59, 0xbfb8aa3b, v59
	v_add_f32_e32 v60, v61, v71
	v_exp_f32_e32 v59, v59
	v_mul_f32_e32 v60, 0xbfb8aa3b, v60
	v_exp_f32_e32 v60, v60
	v_add_f32_e32 v59, 1.0, v59
	v_rcp_f32_e32 v59, v59
	v_add_f32_e32 v60, 1.0, v60
	v_rcp_f32_e32 v60, v60
	v_mul_f32_e32 v59, v59, v73
	v_mul_f32_e32 v60, v60, v65
	v_cvt_pk_bf16_f32 v251, v59, v60
	v_lshl_add_u64 v[252:253], v[62:63], 0, v[176:177]
	s_nop 1
	v_permlane16_swap_b32_e32 v248, v250
	v_permlane16_swap_b32_e32 v249, v251
	global_store_dwordx4 v[252:253], v[248:251], off
	s_waitcnt vmcnt(13)
	v_permlane16_swap_b32_e32 v150, v152
	v_permlane16_swap_b32_e32 v151, v153
	v_mov_b64_e32 v[64:65], v[150:151]
	ds_read_b128 v[58:61], v172 offset:128
	v_lshlrev_b32_e32 v68, 16, v64
	s_waitcnt lgkmcnt(0)
	v_add_f32_e32 v54, v54, v58
	v_add_f32_e32 v55, v55, v59
	v_mul_f32_e32 v54, 0xbfb8aa3b, v54
	v_mul_f32_e32 v55, 0xbfb8aa3b, v55
	v_exp_f32_e32 v54, v54
	v_exp_f32_e32 v55, v55
	v_and_b32_e32 v64, 0xffff0000, v64
	v_lshlrev_b32_e32 v69, 16, v65
	v_add_f32_e32 v54, 1.0, v54
	v_add_f32_e32 v55, 1.0, v55
	v_rcp_f32_e32 v54, v54
	v_rcp_f32_e32 v55, v55
	v_and_b32_e32 v65, 0xffff0000, v65
	v_mul_f32_e32 v54, v54, v68
	v_mul_f32_e32 v55, v55, v64
	v_cvt_pk_bf16_f32 v248, v54, v55
	v_add_f32_e32 v55, v56, v60
	v_mul_f32_e32 v55, 0xbfb8aa3b, v55
	v_add_f32_e32 v56, v57, v61
	v_exp_f32_e32 v55, v55
	v_mul_f32_e32 v56, 0xbfb8aa3b, v56
	v_exp_f32_e32 v56, v56
	v_add_f32_e32 v55, 1.0, v55
	v_rcp_f32_e32 v55, v55
	v_add_f32_e32 v56, 1.0, v56
	v_rcp_f32_e32 v56, v56
	v_mul_f32_e32 v55, v55, v69
	v_mul_f32_e32 v56, v56, v65
	v_cvt_pk_bf16_f32 v249, v55, v56
	s_waitcnt vmcnt(13)
	v_mov_b64_e32 v[54:55], v[152:153]
	ds_read_b128 v[56:59], v172 offset:192
	v_lshlrev_b32_e32 v60, 16, v54
	s_waitcnt lgkmcnt(0)
	v_add_f32_e32 v50, v50, v56
	v_add_f32_e32 v51, v51, v57
	v_mul_f32_e32 v50, 0xbfb8aa3b, v50
	v_mul_f32_e32 v51, 0xbfb8aa3b, v51
	v_exp_f32_e32 v50, v50
	v_exp_f32_e32 v51, v51
	v_and_b32_e32 v54, 0xffff0000, v54
	v_lshlrev_b32_e32 v61, 16, v55
	v_add_f32_e32 v50, 1.0, v50
	v_add_f32_e32 v51, 1.0, v51
	v_rcp_f32_e32 v50, v50
	v_rcp_f32_e32 v51, v51
	v_and_b32_e32 v55, 0xffff0000, v55
	v_mul_f32_e32 v50, v50, v60
	v_mul_f32_e32 v51, v51, v54
	v_cvt_pk_bf16_f32 v250, v50, v51
	v_add_f32_e32 v51, v52, v58
	v_mul_f32_e32 v51, 0xbfb8aa3b, v51
	v_add_f32_e32 v52, v53, v59
	v_exp_f32_e32 v51, v51
	v_mul_f32_e32 v52, 0xbfb8aa3b, v52
	v_exp_f32_e32 v52, v52
	v_add_f32_e32 v51, 1.0, v51
	v_rcp_f32_e32 v51, v51
	v_add_f32_e32 v52, 1.0, v52
	v_rcp_f32_e32 v52, v52
	v_mul_f32_e32 v51, v51, v61
	v_mul_f32_e32 v52, v52, v55
	v_cvt_pk_bf16_f32 v251, v51, v52
	v_lshl_add_u64 v[252:253], v[62:63], 0, v[176:177]
	s_nop 1
	v_permlane16_swap_b32_e32 v248, v250
	v_permlane16_swap_b32_e32 v249, v251
	global_store_dwordx4 v[252:253], v[248:251], off offset:64
	v_lshl_add_u64 v[50:51], s[24:25], 0, v[206:207]
	v_lshl_add_u64 v[50:51], v[50:51], 0, v[0:1]
	s_waitcnt vmcnt(12)
	v_permlane16_swap_b32_e32 v154, v156
	v_permlane16_swap_b32_e32 v155, v157
	v_mov_b64_e32 v[56:57], v[154:155]
	ds_read_b128 v[52:55], v172
	v_lshlrev_b32_e32 v58, 16, v56
	s_waitcnt lgkmcnt(0)
	v_add_f32_e32 v46, v46, v52
	v_add_f32_e32 v47, v47, v53
	v_mul_f32_e32 v46, 0xbfb8aa3b, v46
	v_mul_f32_e32 v47, 0xbfb8aa3b, v47
	v_exp_f32_e32 v46, v46
	v_exp_f32_e32 v47, v47
	v_and_b32_e32 v56, 0xffff0000, v56
	v_lshlrev_b32_e32 v59, 16, v57
	v_add_f32_e32 v46, 1.0, v46
	v_add_f32_e32 v47, 1.0, v47
	v_rcp_f32_e32 v46, v46
	v_rcp_f32_e32 v47, v47
	v_and_b32_e32 v57, 0xffff0000, v57
	v_mul_f32_e32 v46, v46, v58
	v_mul_f32_e32 v47, v47, v56
	v_cvt_pk_bf16_f32 v248, v46, v47
	v_add_f32_e32 v46, v48, v54
	v_add_f32_e32 v47, v49, v55
	v_mul_f32_e32 v46, 0xbfb8aa3b, v46
	v_mul_f32_e32 v47, 0xbfb8aa3b, v47
	v_exp_f32_e32 v46, v46
	v_exp_f32_e32 v47, v47
	v_add_f32_e32 v46, 1.0, v46
	v_add_f32_e32 v47, 1.0, v47
	v_rcp_f32_e32 v46, v46
	v_rcp_f32_e32 v47, v47
	v_mul_f32_e32 v46, v46, v59
	v_mul_f32_e32 v47, v47, v57
	v_cvt_pk_bf16_f32 v249, v46, v47
	v_lshl_add_u64 v[46:47], s[22:23], 0, v[206:207]
	v_lshl_add_u64 v[46:47], v[46:47], 0, v[0:1]
	s_waitcnt vmcnt(12)
	v_mov_b64_e32 v[48:49], v[156:157]
	ds_read_b128 v[52:55], v172 offset:64
	v_lshlrev_b32_e32 v56, 16, v48
	s_waitcnt lgkmcnt(0)
	v_add_f32_e32 v42, v42, v52
	v_add_f32_e32 v43, v43, v53
	v_mul_f32_e32 v42, 0xbfb8aa3b, v42
	v_mul_f32_e32 v43, 0xbfb8aa3b, v43
	v_exp_f32_e32 v42, v42
	v_exp_f32_e32 v43, v43
	v_and_b32_e32 v48, 0xffff0000, v48
	v_lshlrev_b32_e32 v57, 16, v49
	v_add_f32_e32 v42, 1.0, v42
	v_add_f32_e32 v43, 1.0, v43
	v_rcp_f32_e32 v42, v42
	v_rcp_f32_e32 v43, v43
	v_and_b32_e32 v49, 0xffff0000, v49
	v_mul_f32_e32 v42, v42, v56
	v_mul_f32_e32 v43, v43, v48
	v_cvt_pk_bf16_f32 v250, v42, v43
	v_add_f32_e32 v43, v44, v54
	v_mul_f32_e32 v43, 0xbfb8aa3b, v43
	v_add_f32_e32 v44, v45, v55
	v_exp_f32_e32 v43, v43
	v_mul_f32_e32 v44, 0xbfb8aa3b, v44
	v_exp_f32_e32 v44, v44
	v_add_f32_e32 v43, 1.0, v43
	v_rcp_f32_e32 v43, v43
	v_add_f32_e32 v44, 1.0, v44
	v_rcp_f32_e32 v44, v44
	v_mul_f32_e32 v43, v43, v57
	v_mul_f32_e32 v44, v44, v49
	v_cvt_pk_bf16_f32 v251, v43, v44
	v_lshl_add_u64 v[252:253], v[46:47], 0, v[176:177]
	s_nop 1
	v_permlane16_swap_b32_e32 v248, v250
	v_permlane16_swap_b32_e32 v249, v251
	global_store_dwordx4 v[252:253], v[248:251], off
	s_waitcnt vmcnt(11)
	v_permlane16_swap_b32_e32 v158, v160
	v_permlane16_swap_b32_e32 v159, v161
	v_mov_b64_e32 v[48:49], v[158:159]
	ds_read_b128 v[42:45], v172 offset:128
	v_lshlrev_b32_e32 v52, 16, v48
	s_waitcnt lgkmcnt(0)
	v_add_f32_e32 v38, v38, v42
	v_add_f32_e32 v39, v39, v43
	v_mul_f32_e32 v38, 0xbfb8aa3b, v38
	v_mul_f32_e32 v39, 0xbfb8aa3b, v39
	v_exp_f32_e32 v38, v38
	v_exp_f32_e32 v39, v39
	v_and_b32_e32 v48, 0xffff0000, v48
	v_lshlrev_b32_e32 v53, 16, v49
	v_add_f32_e32 v38, 1.0, v38
	v_add_f32_e32 v39, 1.0, v39
	v_rcp_f32_e32 v38, v38
	v_rcp_f32_e32 v39, v39
	v_and_b32_e32 v49, 0xffff0000, v49
	v_mul_f32_e32 v38, v38, v52
	v_mul_f32_e32 v39, v39, v48
	v_cvt_pk_bf16_f32 v248, v38, v39
	v_add_f32_e32 v39, v40, v44
	v_mul_f32_e32 v39, 0xbfb8aa3b, v39
	v_add_f32_e32 v40, v41, v45
	v_exp_f32_e32 v39, v39
	v_mul_f32_e32 v40, 0xbfb8aa3b, v40
	v_exp_f32_e32 v40, v40
	v_add_f32_e32 v39, 1.0, v39
	v_rcp_f32_e32 v39, v39
	v_add_f32_e32 v40, 1.0, v40
	v_rcp_f32_e32 v40, v40
	v_mul_f32_e32 v39, v39, v53
	v_mul_f32_e32 v40, v40, v49
	v_cvt_pk_bf16_f32 v249, v39, v40
	s_waitcnt vmcnt(11)
	v_mov_b64_e32 v[38:39], v[160:161]
	ds_read_b128 v[40:43], v172 offset:192
	v_lshlrev_b32_e32 v44, 16, v38
	s_waitcnt lgkmcnt(0)
	v_add_f32_e32 v34, v34, v40
	v_add_f32_e32 v35, v35, v41
	v_mul_f32_e32 v34, 0xbfb8aa3b, v34
	v_mul_f32_e32 v35, 0xbfb8aa3b, v35
	v_exp_f32_e32 v34, v34
	v_exp_f32_e32 v35, v35
	v_and_b32_e32 v38, 0xffff0000, v38
	v_lshlrev_b32_e32 v45, 16, v39
	v_add_f32_e32 v34, 1.0, v34
	v_add_f32_e32 v35, 1.0, v35
	v_rcp_f32_e32 v34, v34
	v_rcp_f32_e32 v35, v35
	v_and_b32_e32 v39, 0xffff0000, v39
	v_mul_f32_e32 v34, v34, v44
	v_mul_f32_e32 v35, v35, v38
	v_cvt_pk_bf16_f32 v250, v34, v35
	v_add_f32_e32 v35, v36, v42
	v_mul_f32_e32 v35, 0xbfb8aa3b, v35
	v_add_f32_e32 v36, v37, v43
	v_exp_f32_e32 v35, v35
	v_mul_f32_e32 v36, 0xbfb8aa3b, v36
	v_exp_f32_e32 v36, v36
	v_add_f32_e32 v35, 1.0, v35
	v_rcp_f32_e32 v35, v35
	v_add_f32_e32 v36, 1.0, v36
	v_rcp_f32_e32 v36, v36
	v_mul_f32_e32 v35, v35, v45
	v_mul_f32_e32 v36, v36, v39
	v_cvt_pk_bf16_f32 v251, v35, v36
	v_lshl_add_u64 v[252:253], v[46:47], 0, v[176:177]
	s_nop 1
	v_permlane16_swap_b32_e32 v248, v250
	v_permlane16_swap_b32_e32 v249, v251
	global_store_dwordx4 v[252:253], v[248:251], off offset:64
	v_lshl_add_u64 v[34:35], s[24:25], 0, v[208:209]
	v_lshl_add_u64 v[34:35], v[34:35], 0, v[0:1]
	s_waitcnt vmcnt(10)
	v_permlane16_swap_b32_e32 v162, v164
	v_permlane16_swap_b32_e32 v163, v165
	v_mov_b64_e32 v[40:41], v[162:163]
	ds_read_b128 v[36:39], v172
	v_lshlrev_b32_e32 v42, 16, v40
	s_waitcnt lgkmcnt(0)
	v_add_f32_e32 v30, v30, v36
	v_add_f32_e32 v31, v31, v37
	v_mul_f32_e32 v30, 0xbfb8aa3b, v30
	v_mul_f32_e32 v31, 0xbfb8aa3b, v31
	v_exp_f32_e32 v30, v30
	v_exp_f32_e32 v31, v31
	v_and_b32_e32 v40, 0xffff0000, v40
	v_lshlrev_b32_e32 v43, 16, v41
	v_add_f32_e32 v30, 1.0, v30
	v_add_f32_e32 v31, 1.0, v31
	v_rcp_f32_e32 v30, v30
	v_rcp_f32_e32 v31, v31
	v_and_b32_e32 v41, 0xffff0000, v41
	v_mul_f32_e32 v30, v30, v42
	v_mul_f32_e32 v31, v31, v40
	v_cvt_pk_bf16_f32 v248, v30, v31
	v_add_f32_e32 v30, v32, v38
	v_add_f32_e32 v31, v33, v39
	v_mul_f32_e32 v30, 0xbfb8aa3b, v30
	v_mul_f32_e32 v31, 0xbfb8aa3b, v31
	v_exp_f32_e32 v30, v30
	v_exp_f32_e32 v31, v31
	v_add_f32_e32 v30, 1.0, v30
	v_add_f32_e32 v31, 1.0, v31
	v_rcp_f32_e32 v30, v30
	v_rcp_f32_e32 v31, v31
	v_mul_f32_e32 v30, v30, v43
	v_mul_f32_e32 v31, v31, v41
	v_cvt_pk_bf16_f32 v249, v30, v31
	v_lshl_add_u64 v[30:31], s[22:23], 0, v[208:209]
	v_lshl_add_u64 v[30:31], v[30:31], 0, v[0:1]
	s_waitcnt vmcnt(10)
	v_mov_b64_e32 v[32:33], v[164:165]
	ds_read_b128 v[36:39], v172 offset:64
	v_lshlrev_b32_e32 v40, 16, v32
	s_waitcnt lgkmcnt(0)
	v_add_f32_e32 v26, v26, v36
	v_add_f32_e32 v27, v27, v37
	v_mul_f32_e32 v26, 0xbfb8aa3b, v26
	v_mul_f32_e32 v27, 0xbfb8aa3b, v27
	v_exp_f32_e32 v26, v26
	v_exp_f32_e32 v27, v27
	v_and_b32_e32 v32, 0xffff0000, v32
	v_lshlrev_b32_e32 v41, 16, v33
	v_add_f32_e32 v26, 1.0, v26
	v_add_f32_e32 v27, 1.0, v27
	v_rcp_f32_e32 v26, v26
	v_rcp_f32_e32 v27, v27
	v_and_b32_e32 v33, 0xffff0000, v33
	v_mul_f32_e32 v26, v26, v40
	v_mul_f32_e32 v27, v27, v32
	v_cvt_pk_bf16_f32 v250, v26, v27
	v_add_f32_e32 v27, v28, v38
	v_mul_f32_e32 v27, 0xbfb8aa3b, v27
	v_add_f32_e32 v28, v29, v39
	v_exp_f32_e32 v27, v27
	v_mul_f32_e32 v28, 0xbfb8aa3b, v28
	v_exp_f32_e32 v28, v28
	v_add_f32_e32 v27, 1.0, v27
	v_rcp_f32_e32 v27, v27
	v_add_f32_e32 v28, 1.0, v28
	v_rcp_f32_e32 v28, v28
	v_mul_f32_e32 v27, v27, v41
	v_mul_f32_e32 v28, v28, v33
	v_cvt_pk_bf16_f32 v251, v27, v28
	v_lshl_add_u64 v[252:253], v[30:31], 0, v[176:177]
	s_nop 1
	v_permlane16_swap_b32_e32 v248, v250
	v_permlane16_swap_b32_e32 v249, v251
	global_store_dwordx4 v[252:253], v[248:251], off
	s_waitcnt vmcnt(9)
	v_permlane16_swap_b32_e32 v166, v168
	v_permlane16_swap_b32_e32 v167, v169
	v_mov_b64_e32 v[32:33], v[166:167]
	ds_read_b128 v[26:29], v172 offset:128
	v_lshlrev_b32_e32 v36, 16, v32
	s_waitcnt lgkmcnt(0)
	v_add_f32_e32 v22, v22, v26
	v_add_f32_e32 v23, v23, v27
	v_mul_f32_e32 v22, 0xbfb8aa3b, v22
	v_mul_f32_e32 v23, 0xbfb8aa3b, v23
	v_exp_f32_e32 v22, v22
	v_exp_f32_e32 v23, v23
	v_and_b32_e32 v32, 0xffff0000, v32
	v_lshlrev_b32_e32 v37, 16, v33
	v_add_f32_e32 v22, 1.0, v22
	v_add_f32_e32 v23, 1.0, v23
	v_rcp_f32_e32 v22, v22
	v_rcp_f32_e32 v23, v23
	v_and_b32_e32 v33, 0xffff0000, v33
	v_mul_f32_e32 v22, v22, v36
	v_mul_f32_e32 v23, v23, v32
	v_cvt_pk_bf16_f32 v248, v22, v23
	v_add_f32_e32 v23, v24, v28
	v_mul_f32_e32 v23, 0xbfb8aa3b, v23
	v_add_f32_e32 v24, v25, v29
	v_exp_f32_e32 v23, v23
	v_mul_f32_e32 v24, 0xbfb8aa3b, v24
	v_exp_f32_e32 v24, v24
	v_add_f32_e32 v23, 1.0, v23
	v_rcp_f32_e32 v23, v23
	v_add_f32_e32 v24, 1.0, v24
	v_rcp_f32_e32 v24, v24
	v_mul_f32_e32 v23, v23, v37
	v_mul_f32_e32 v24, v24, v33
	v_cvt_pk_bf16_f32 v249, v23, v24
	s_waitcnt vmcnt(9)
; template <class DescFn, class EpiFn>
; __device__ __forceinline__ void gemm_phase(int nM, int nN, DescFn dfn, EpiFn efn) {
;     ...
;     efn(cpm, cpn)(acc, wr, wc, fr, fq);
;     if (!more) break;
	v_mov_b64_e32 v[22:23], v[168:169]
	ds_read_b128 v[24:27], v172 offset:192
	v_lshlrev_b32_e32 v28, 16, v22
	s_waitcnt lgkmcnt(0)
	v_add_f32_e32 v18, v18, v24
	v_add_f32_e32 v19, v19, v25
	v_mul_f32_e32 v18, 0xbfb8aa3b, v18
	v_mul_f32_e32 v19, 0xbfb8aa3b, v19
	v_exp_f32_e32 v18, v18
	v_exp_f32_e32 v19, v19
	v_and_b32_e32 v22, 0xffff0000, v22
	v_lshlrev_b32_e32 v29, 16, v23
	v_add_f32_e32 v18, 1.0, v18
	v_add_f32_e32 v19, 1.0, v19
	v_rcp_f32_e32 v18, v18
	v_rcp_f32_e32 v19, v19
	v_and_b32_e32 v23, 0xffff0000, v23
	v_mul_f32_e32 v18, v18, v28
	v_mul_f32_e32 v19, v19, v22
	v_cvt_pk_bf16_f32 v250, v18, v19
	v_add_f32_e32 v19, v20, v26
	v_mul_f32_e32 v19, 0xbfb8aa3b, v19
	v_add_f32_e32 v20, v21, v27
	v_exp_f32_e32 v19, v19
	v_mul_f32_e32 v20, 0xbfb8aa3b, v20
	v_exp_f32_e32 v20, v20
	v_add_f32_e32 v19, 1.0, v19
	v_rcp_f32_e32 v19, v19
	v_add_f32_e32 v20, 1.0, v20
	v_rcp_f32_e32 v20, v20
	v_mul_f32_e32 v19, v19, v29
	v_mul_f32_e32 v20, v20, v23
	v_cvt_pk_bf16_f32 v251, v19, v20
	v_lshl_add_u64 v[252:253], v[30:31], 0, v[176:177]
	s_nop 1
	v_permlane16_swap_b32_e32 v248, v250
	v_permlane16_swap_b32_e32 v249, v251
	global_store_dwordx4 v[252:253], v[248:251], off offset:64
	v_lshl_add_u64 v[18:19], s[24:25], 0, v[210:211]
	v_lshl_add_u64 v[18:19], v[18:19], 0, v[0:1]
	s_waitcnt vmcnt(8)
	v_permlane16_swap_b32_e32 v142, v144
	v_permlane16_swap_b32_e32 v143, v145
	v_mov_b64_e32 v[24:25], v[142:143]
	ds_read_b128 v[20:23], v172
	v_lshlrev_b32_e32 v26, 16, v24
	s_waitcnt lgkmcnt(0)
	v_add_f32_e32 v14, v14, v20
	v_add_f32_e32 v15, v15, v21
	v_mul_f32_e32 v14, 0xbfb8aa3b, v14
	v_mul_f32_e32 v15, 0xbfb8aa3b, v15
	v_exp_f32_e32 v14, v14
	v_exp_f32_e32 v15, v15
	v_and_b32_e32 v24, 0xffff0000, v24
	v_lshlrev_b32_e32 v27, 16, v25
	v_add_f32_e32 v14, 1.0, v14
	v_add_f32_e32 v15, 1.0, v15
	v_rcp_f32_e32 v14, v14
	v_rcp_f32_e32 v15, v15
	v_and_b32_e32 v25, 0xffff0000, v25
	v_mul_f32_e32 v14, v14, v26
	v_mul_f32_e32 v15, v15, v24
	v_cvt_pk_bf16_f32 v248, v14, v15
	v_add_f32_e32 v14, v16, v22
	v_add_f32_e32 v15, v17, v23
	v_mul_f32_e32 v14, 0xbfb8aa3b, v14
	v_mul_f32_e32 v15, 0xbfb8aa3b, v15
	v_exp_f32_e32 v14, v14
	v_exp_f32_e32 v15, v15
	v_add_f32_e32 v14, 1.0, v14
	v_add_f32_e32 v15, 1.0, v15
	v_rcp_f32_e32 v14, v14
	v_rcp_f32_e32 v15, v15
	v_mul_f32_e32 v14, v14, v27
	v_mul_f32_e32 v15, v15, v25
	v_cvt_pk_bf16_f32 v249, v14, v15
	v_lshl_add_u64 v[14:15], s[22:23], 0, v[210:211]
	v_lshl_add_u64 v[14:15], v[14:15], 0, v[0:1]
	s_waitcnt vmcnt(8)
	v_mov_b64_e32 v[16:17], v[144:145]
	ds_read_b128 v[20:23], v172 offset:64
	v_lshlrev_b32_e32 v0, 16, v16
	s_waitcnt lgkmcnt(0)
	v_add_f32_e32 v10, v10, v20
	v_mul_f32_e32 v10, 0xbfb8aa3b, v10
	v_exp_f32_e32 v10, v10
	v_and_b32_e32 v16, 0xffff0000, v16
	v_lshlrev_b32_e32 v24, 16, v17
	v_and_b32_e32 v17, 0xffff0000, v17
	v_add_f32_e32 v10, 1.0, v10
	v_rcp_f32_e32 v10, v10
	s_nop 0
	v_mul_f32_e32 v0, v10, v0
	v_add_f32_e32 v10, v11, v21
	v_mul_f32_e32 v10, 0xbfb8aa3b, v10
	v_exp_f32_e32 v10, v10
	v_add_f32_e32 v11, v13, v23
	v_mul_f32_e32 v11, 0xbfb8aa3b, v11
	v_exp_f32_e32 v11, v11
	v_add_f32_e32 v10, 1.0, v10
	v_rcp_f32_e32 v10, v10
	v_add_f32_e32 v11, 1.0, v11
	v_rcp_f32_e32 v11, v11
	v_mul_f32_e32 v10, v10, v16
	v_cvt_pk_bf16_f32 v250, v0, v10
	v_add_f32_e32 v0, v12, v22
	v_mul_f32_e32 v0, 0xbfb8aa3b, v0
	v_exp_f32_e32 v0, v0
	v_mul_f32_e32 v11, v11, v17
	v_add_f32_e32 v0, 1.0, v0
	v_rcp_f32_e32 v0, v0
	s_nop 0
	v_mul_f32_e32 v0, v0, v24
	v_cvt_pk_bf16_f32 v251, v0, v11
	v_lshl_add_u64 v[252:253], v[14:15], 0, v[176:177]
	s_nop 1
	v_permlane16_swap_b32_e32 v248, v250
	v_permlane16_swap_b32_e32 v249, v251
	global_store_dwordx4 v[252:253], v[248:251], off
	s_waitcnt vmcnt(7)
	v_permlane16_swap_b32_e32 v146, v148
	v_permlane16_swap_b32_e32 v147, v149
	v_mov_b64_e32 v[16:17], v[146:147]
	ds_read_b128 v[10:13], v172 offset:128
	v_lshlrev_b32_e32 v0, 16, v16
	s_waitcnt lgkmcnt(0)
	v_add_f32_e32 v6, v6, v10
	v_mul_f32_e32 v6, 0xbfb8aa3b, v6
	v_exp_f32_e32 v6, v6
	v_and_b32_e32 v16, 0xffff0000, v16
	v_lshlrev_b32_e32 v20, 16, v17
	v_and_b32_e32 v17, 0xffff0000, v17
	v_add_f32_e32 v6, 1.0, v6
	v_rcp_f32_e32 v6, v6
	s_nop 0
	v_mul_f32_e32 v0, v6, v0
	v_add_f32_e32 v6, v7, v11
	v_mul_f32_e32 v6, 0xbfb8aa3b, v6
	v_exp_f32_e32 v6, v6
	v_add_f32_e32 v7, v9, v13
	v_mul_f32_e32 v7, 0xbfb8aa3b, v7
	v_exp_f32_e32 v7, v7
	v_add_f32_e32 v6, 1.0, v6
	v_rcp_f32_e32 v6, v6
	v_add_f32_e32 v7, 1.0, v7
	v_rcp_f32_e32 v7, v7
	v_mul_f32_e32 v6, v6, v16
	v_cvt_pk_bf16_f32 v248, v0, v6
	v_add_f32_e32 v0, v8, v12
	v_mul_f32_e32 v0, 0xbfb8aa3b, v0
	v_exp_f32_e32 v0, v0
	v_mul_f32_e32 v7, v7, v17
	v_add_f32_e32 v0, 1.0, v0
	v_rcp_f32_e32 v0, v0
	s_nop 0
	v_mul_f32_e32 v0, v0, v20
	v_cvt_pk_bf16_f32 v249, v0, v7
	s_waitcnt vmcnt(7)
	v_mov_b64_e32 v[6:7], v[148:149]
	ds_read_b128 v[8:11], v172 offset:192
	v_lshlrev_b32_e32 v0, 16, v6
	s_waitcnt lgkmcnt(0)
	v_add_f32_e32 v2, v2, v8
	v_mul_f32_e32 v2, 0xbfb8aa3b, v2
	v_exp_f32_e32 v2, v2
	v_and_b32_e32 v6, 0xffff0000, v6
	v_lshlrev_b32_e32 v12, 16, v7
	v_and_b32_e32 v7, 0xffff0000, v7
	v_add_f32_e32 v2, 1.0, v2
	v_rcp_f32_e32 v2, v2
	s_nop 0
	v_mul_f32_e32 v0, v2, v0
	v_add_f32_e32 v2, v3, v9
	v_mul_f32_e32 v2, 0xbfb8aa3b, v2
	v_exp_f32_e32 v2, v2
	v_add_f32_e32 v3, v5, v11
	v_mul_f32_e32 v3, 0xbfb8aa3b, v3
	v_exp_f32_e32 v3, v3
	v_add_f32_e32 v2, 1.0, v2
	v_rcp_f32_e32 v2, v2
	v_add_f32_e32 v3, 1.0, v3
	v_rcp_f32_e32 v3, v3
	v_mul_f32_e32 v2, v2, v6
	v_cvt_pk_bf16_f32 v250, v0, v2
	v_add_f32_e32 v0, v4, v10
	v_mul_f32_e32 v0, 0xbfb8aa3b, v0
	v_exp_f32_e32 v0, v0
	v_mul_f32_e32 v3, v3, v7
	v_add_f32_e32 v0, 1.0, v0
	v_rcp_f32_e32 v0, v0
	s_nop 0
	v_mul_f32_e32 v0, v0, v12
	v_cvt_pk_bf16_f32 v251, v0, v3
	v_lshl_add_u64 v[252:253], v[14:15], 0, v[176:177]
	s_nop 1
	v_permlane16_swap_b32_e32 v248, v250
	v_permlane16_swap_b32_e32 v249, v251
	global_store_dwordx4 v[252:253], v[248:251], off offset:64
	s_setprio 0
	s_andn2_b64 vcc, exec, s[18:19]
	s_mov_b64 s[18:19], -1
	s_cbranch_vccnz .LBB0_1384
	s_mov_b64 s[18:19], 0
	s_branch .LBB0_1384
